# v29 + lnstats: 8th row load issued before the wait (no code size change)
# baseline (speedup 1.0000x reference)
; __device__ __forceinline__ float bf_lo(unsigned u) { return __uint_as_float(u << 16); }
; __device__ __forceinline__ float bf_hi(unsigned u) { return __uint_as_float(u & 0xffff0000u); }
; __device__ __forceinline__ void phase_lnstats(const Args& a, int nrows) {
;     ...
;     for (int row0 = gw; row0 < nrows; row0 += 2 * NGW) {
;         u32x4 w[2][4]; int rows[2]; rows[0] = row0; rows[1] = row0 + NGW; const bool ok1 = rows[1] < nrows; if (!ok1) rows[1] = row0;
; #pragma unroll
;         for (int u = 0; u < 2; ++u) { const bf16_t* zr = Z + (size_t)rows[u] * SGUW + SGUH;
; #pragma unroll
;             for (int j = 0; j < 4; ++j) w[u][j] = *(const u32x4*)(zr + 8 * lane + 512 * j); }
; #pragma unroll
;         for (int u = 0; u < 2; ++u) { if (u == 1 && !ok1) continue;
;             float v[32]; float s = 0.f;
; #pragma unroll
;             for (int j = 0; j < 4; ++j) { const u32x4 x = w[u][j];
;                 v[8 * j + 0] = bf_lo(x.x); v[8 * j + 1] = bf_hi(x.x); v[8 * j + 2] = bf_lo(x.y); v[8 * j + 3] = bf_hi(x.y); v[8 * j + 4] = bf_lo(x.z); v[8 * j + 5] = bf_hi(x.z); v[8 * j + 6] = bf_lo(x.w); v[8 * j + 7] = bf_hi(x.w); }
; #pragma unroll
;             for (int i = 0; i < 32; ++i) s += v[i];
;             const float mu = wave_sum(s) * (1.f / SGUH); float q = 0.f;
; #pragma unroll
;             for (int i = 0; i < 32; ++i) { const float d = v[i] - mu; q += d * d; }
;             const float rstd = rsqrtf(wave_sum(q) * (1.f / SGUH) + EPS);
;             if (lane == 0) { st[2 * rows[u]] = mu; st[2 * rows[u] + 1] = rstd; } }
.LBB0_260:
	v_add_u32_e32 v28, s0, v20
	v_cmp_gt_i32_e64 s[38:39], s62, v28
	s_waitcnt lgkmcnt(0)
	v_ashrrev_i32_e32 v21, 31, v20
	s_mov_b32 s8, 0xf301000
	v_cndmask_b32_e64 v2, v20, v28, s[38:39]
	v_ashrrev_i32_e32 v3, 31, v2
	v_lshlrev_b64 v[2:3], 13, v[2:3]
	v_lshl_add_u64 v[2:3], s[70:71], 0, v[2:3]
	v_lshl_add_u64 v[2:3], v[2:3], 0, v[0:1]
	v_lshlrev_b64 v[20:21], 13, v[20:21]
	v_lshl_add_u64 v[4:5], v[2:3], 0, s[16:17]
	v_add_co_u32_e32 v2, vcc, 0xf301000, v2
	v_lshl_add_u64 v[20:21], s[70:71], 0, v[20:21]
	s_nop 0
	v_addc_co_u32_e32 v3, vcc, 0, v3, vcc
	v_lshl_add_u64 v[20:21], v[20:21], 0, v[0:1]
	v_lshl_add_u64 v[38:39], v[20:21], 0, s[16:17]
	v_add_co_u32_e32 v20, vcc, s8, v20
	global_load_dwordx4 v[14:17], v[2:3], off
	global_load_dwordx4 v[10:13], v[4:5], off offset:1024
	global_load_dwordx4 v[6:9], v[4:5], off offset:2048
	s_nop 0
	global_load_dwordx4 v[2:5], v[4:5], off offset:3072
	v_addc_co_u32_e32 v21, vcc, 0, v21, vcc
	global_load_dwordx4 v[30:33], v[38:39], off offset:3072
	global_load_dwordx4 v[34:37], v[38:39], off offset:2048
	s_nop 0
	global_load_dwordx4 v[38:41], v[38:39], off offset:1024
	global_load_dwordx4 v[42:45], v[20:21], off
	s_waitcnt vmcnt(0)
	v_lshlrev_b32_e32 v55, 16, v30
	v_lshlrev_b32_e32 v47, 16, v38
	v_and_b32_e32 v38, 0xffff0000, v38
	v_lshlrev_b32_e32 v48, 16, v39
	v_and_b32_e32 v39, 0xffff0000, v39
	v_lshlrev_b32_e32 v49, 16, v40
	v_and_b32_e32 v40, 0xffff0000, v40
	v_lshlrev_b32_e32 v50, 16, v41
	v_and_b32_e32 v41, 0xffff0000, v41
	v_lshlrev_b32_e32 v51, 16, v34
	v_and_b32_e32 v34, 0xffff0000, v34
	v_lshlrev_b32_e32 v52, 16, v35
	v_and_b32_e32 v35, 0xffff0000, v35
	v_lshlrev_b32_e32 v53, 16, v36
	v_and_b32_e32 v36, 0xffff0000, v36
	v_lshlrev_b32_e32 v54, 16, v37
	v_and_b32_e32 v37, 0xffff0000, v37
	v_and_b32_e32 v30, 0xffff0000, v30
	v_lshlrev_b32_e32 v56, 16, v31
	v_and_b32_e32 v31, 0xffff0000, v31
	v_lshlrev_b32_e32 v57, 16, v32
	v_and_b32_e32 v32, 0xffff0000, v32
	v_lshlrev_b32_e32 v58, 16, v33
	v_and_b32_e32 v33, 0xffff0000, v33
	s_waitcnt vmcnt(0)
	v_lshlrev_b32_e32 v20, 16, v42
	v_and_b32_e32 v21, 0xffff0000, v42
	v_add_f32_e32 v19, 0, v20
	v_lshlrev_b32_e32 v29, 16, v43
	v_add_f32_e32 v19, v19, v21
	v_and_b32_e32 v42, 0xffff0000, v43
	v_add_f32_e32 v19, v19, v29
	v_lshlrev_b32_e32 v43, 16, v44
	v_add_f32_e32 v19, v19, v42
	v_and_b32_e32 v44, 0xffff0000, v44
	v_add_f32_e32 v19, v19, v43
	v_lshlrev_b32_e32 v46, 16, v45
	v_add_f32_e32 v19, v19, v44
	v_and_b32_e32 v45, 0xffff0000, v45
	v_add_f32_e32 v19, v19, v46
	v_add_f32_e32 v19, v19, v45
	v_add_f32_e32 v19, v19, v47
	v_add_f32_e32 v19, v19, v38
	v_add_f32_e32 v19, v19, v48
	v_add_f32_e32 v19, v19, v39
	v_add_f32_e32 v19, v19, v49
	v_add_f32_e32 v19, v19, v40
	v_add_f32_e32 v19, v19, v50
	v_add_f32_e32 v19, v19, v41
	v_add_f32_e32 v19, v19, v51
	v_add_f32_e32 v19, v19, v34
	v_add_f32_e32 v19, v19, v52
	v_add_f32_e32 v19, v19, v35
	v_add_f32_e32 v19, v19, v53
	v_add_f32_e32 v19, v19, v36
	v_add_f32_e32 v19, v19, v54
	v_add_f32_e32 v19, v19, v37
	v_add_f32_e32 v19, v19, v55
	v_add_f32_e32 v19, v19, v30
	v_add_f32_e32 v19, v19, v56
	v_add_f32_e32 v19, v19, v31
	v_add_f32_e32 v19, v19, v57
	v_add_f32_e32 v19, v19, v32
	v_add_f32_e32 v19, v19, v58
	v_add_f32_e32 v19, v19, v33
	ds_bpermute_b32 v59, v22, v19
	s_waitcnt lgkmcnt(0)
	v_add_f32_e32 v19, v19, v59
	ds_bpermute_b32 v59, v23, v19
	s_waitcnt lgkmcnt(0)
	v_add_f32_e32 v19, v19, v59
	ds_bpermute_b32 v59, v24, v19
	s_waitcnt lgkmcnt(0)
	v_add_f32_e32 v19, v19, v59
	ds_bpermute_b32 v59, v25, v19
	s_waitcnt lgkmcnt(0)
	v_add_f32_e32 v19, v19, v59
	ds_bpermute_b32 v59, v26, v19
	s_waitcnt lgkmcnt(0)
	v_add_f32_e32 v19, v19, v59
	ds_bpermute_b32 v59, v27, v19
	s_waitcnt lgkmcnt(0)
	v_add_f32_e32 v19, v19, v59
	v_fmac_f32_e32 v21, 0xba000000, v19
	v_fmac_f32_e32 v20, 0xba000000, v19
	v_mul_f32_e32 v21, v21, v21
	v_fmac_f32_e32 v21, v20, v20
	v_fmac_f32_e32 v29, 0xba000000, v19
	v_fmac_f32_e32 v21, v29, v29
	v_fmac_f32_e32 v42, 0xba000000, v19
	v_fmac_f32_e32 v21, v42, v42
	v_fmac_f32_e32 v43, 0xba000000, v19
	v_fmac_f32_e32 v21, v43, v43
	v_fmac_f32_e32 v44, 0xba000000, v19
	v_fmac_f32_e32 v21, v44, v44
	v_fmac_f32_e32 v46, 0xba000000, v19
	v_fmac_f32_e32 v21, v46, v46
	v_fmac_f32_e32 v45, 0xba000000, v19
	v_fmac_f32_e32 v21, v45, v45
	v_fmac_f32_e32 v47, 0xba000000, v19
	v_fmac_f32_e32 v21, v47, v47
	v_fmac_f32_e32 v38, 0xba000000, v19
	v_fmac_f32_e32 v21, v38, v38
	v_fmac_f32_e32 v48, 0xba000000, v19
	v_fmac_f32_e32 v21, v48, v48
	v_fmac_f32_e32 v39, 0xba000000, v19
	v_fmac_f32_e32 v21, v39, v39
	v_fmac_f32_e32 v49, 0xba000000, v19
	v_fmac_f32_e32 v21, v49, v49
	v_fmac_f32_e32 v40, 0xba000000, v19
	v_fmac_f32_e32 v21, v40, v40
	v_fmac_f32_e32 v50, 0xba000000, v19
	v_fmac_f32_e32 v21, v50, v50
	v_fmac_f32_e32 v41, 0xba000000, v19
	v_fmac_f32_e32 v21, v41, v41
	v_fmac_f32_e32 v51, 0xba000000, v19
	v_fmac_f32_e32 v21, v51, v51
	v_fmac_f32_e32 v34, 0xba000000, v19
	v_fmac_f32_e32 v21, v34, v34
	v_fmac_f32_e32 v52, 0xba000000, v19
	v_fmac_f32_e32 v21, v52, v52
	v_fmac_f32_e32 v35, 0xba000000, v19
	v_fmac_f32_e32 v21, v35, v35
	v_fmac_f32_e32 v53, 0xba000000, v19
	v_fmac_f32_e32 v21, v53, v53
	v_fmac_f32_e32 v36, 0xba000000, v19
	v_fmac_f32_e32 v21, v36, v36
	v_fmac_f32_e32 v54, 0xba000000, v19
	v_fmac_f32_e32 v21, v54, v54
	v_fmac_f32_e32 v37, 0xba000000, v19
	v_fmac_f32_e32 v21, v37, v37
	v_fmac_f32_e32 v55, 0xba000000, v19
	v_fmac_f32_e32 v21, v55, v55
	v_fmac_f32_e32 v30, 0xba000000, v19
	v_fmac_f32_e32 v21, v30, v30
	v_fmac_f32_e32 v56, 0xba000000, v19
	v_fmac_f32_e32 v21, v56, v56
	v_fmac_f32_e32 v31, 0xba000000, v19
	v_fmac_f32_e32 v21, v31, v31
	v_fmac_f32_e32 v57, 0xba000000, v19
	v_fmac_f32_e32 v21, v57, v57
	v_fmac_f32_e32 v32, 0xba000000, v19
	v_fmac_f32_e32 v21, v32, v32
	v_fmac_f32_e32 v58, 0xba000000, v19
	v_fmac_f32_e32 v21, v58, v58
	v_fmac_f32_e32 v33, 0xba000000, v19
	v_fmac_f32_e32 v21, v33, v33
	ds_bpermute_b32 v20, v22, v21
	s_waitcnt lgkmcnt(0)
	v_add_f32_e32 v20, v21, v20
	ds_bpermute_b32 v21, v23, v20
	s_waitcnt lgkmcnt(0)
	v_add_f32_e32 v20, v20, v21
	ds_bpermute_b32 v21, v24, v20
	s_waitcnt lgkmcnt(0)
	v_add_f32_e32 v20, v20, v21
	ds_bpermute_b32 v21, v25, v20
	s_waitcnt lgkmcnt(0)
	v_add_f32_e32 v20, v20, v21
	ds_bpermute_b32 v21, v26, v20
	s_waitcnt lgkmcnt(0)
	v_add_f32_e32 v20, v20, v21
	ds_bpermute_b32 v21, v27, v20
	s_and_saveexec_b64 s[10:11], s[36:37]
	s_cbranch_execz .LBB0_262
	s_waitcnt lgkmcnt(0)
	v_add_f32_e32 v20, v20, v21
	v_fmamk_f32 v20, v20, 0x3a000000, v215
	v_mul_f32_e32 v21, 0x4b800000, v20
	v_cmp_gt_f32_e32 vcc, s87, v20
	s_nop 1
	v_cndmask_b32_e32 v20, v20, v21, vcc
	v_rsq_f32_e32 v21, v20
	v_mul_f32_e32 v20, 0x3a000000, v19
	v_ashrrev_i32_e32 v19, 31, v18
	v_lshl_add_u64 v[30:31], v[18:19], 2, s[50:51]
	v_mul_f32_e32 v29, 0x45800000, v21
	v_cndmask_b32_e32 v21, v21, v29, vcc
	global_store_dwordx2 v[30:31], v[20:21], off
